# grid barrier poll cadence relaxed (s_sleep 6): fewer poll reads queued in front of the arrival atomics on the shared counter word
# baseline (speedup 1.0000x reference)
; __device__ __forceinline__ unsigned xb_ld(unsigned* p)              { return __hip_atomic_load(p, __ATOMIC_RELAXED, __HIP_MEMORY_SCOPE_AGENT); }
; #define XB_SPIN(cond, bar) do { unsigned _sp = 0; while (cond) { __builtin_amdgcn_s_sleep(1); \
;     if ((++_sp & 255u) == 0u) { if (xb_ld(&(bar)[XB_TMO])) break; if (_sp > XB_SPIN_CAP) { atomicAdd(&(bar)[XB_TMO], 1u); break; } } } } while (0)
; __device__ __forceinline__ void xcd_barrier(const XcdBarrier& b, const bool is_t0) {
;     ...
;             XB_SPIN(xb_ld(&bar[XB_XGEN(b.x)]) == gen, bar);
.Lxb1_spin:
	global_load_dword v5, v202, s[74:75] offset:1024 sc1
	s_waitcnt vmcnt(0)
	v_sub_u32_e32 v5, v5, v4
	v_cmp_gt_i32_e32 vcc, 0, v5
	s_cbranch_vccz .Lxb1_done
	s_sleep 6
	s_add_i32 s18, s18, -1
	s_cmp_lg_u32 s18, 0
	s_cbranch_scc1 .Lxb1_spin

; __device__ __forceinline__ unsigned xb_ld(unsigned* p)              { return __hip_atomic_load(p, __ATOMIC_RELAXED, __HIP_MEMORY_SCOPE_AGENT); }
; #define XB_SPIN(cond, bar) do { unsigned _sp = 0; while (cond) { __builtin_amdgcn_s_sleep(1); \
;     if ((++_sp & 255u) == 0u) { if (xb_ld(&(bar)[XB_TMO])) break; if (_sp > XB_SPIN_CAP) { atomicAdd(&(bar)[XB_TMO], 1u); break; } } } } while (0)
; __device__ __forceinline__ void xcd_barrier(const XcdBarrier& b, const bool is_t0) {
;     ...
;             XB_SPIN(xb_ld(&bar[XB_XGEN(b.x)]) == gen, bar);
.Lxb2_spin:
	global_load_dword v5, v202, s[6:7] offset:1024 sc1
	s_waitcnt vmcnt(0)
	v_sub_u32_e32 v5, v5, v4
	v_cmp_gt_i32_e32 vcc, 0, v5
	s_cbranch_vccz .Lxb2_done
	s_sleep 6
	s_add_i32 s10, s10, -1
	s_cmp_lg_u32 s10, 0
	s_cbranch_scc1 .Lxb2_spin
